# Q + attention softmax row sums by packed f32 VALU adds instead of a ones-matrix PV MFMA (4 of 24 MFMAs per key tile removed)
# baseline (speedup 1.0000x reference)
; #define LAS __attribute__((address_space(3)))
; __device__ __forceinline__ unsigned cvtpk(float lo, float hi) { unsigned r; asm volatile("v_cvt_pk_bf16_f32 %0, %1, %2" : "=v"(r) : "v"(lo), "v"(hi)); return r; }
; __device__ __forceinline__ void attn_unit(const Params& p, LAS unsigned char* lds, int b, int h, int qb, int tid, int wid, int lane, u64& tacc, v4u& kA, v4u& vA, v4u& kB, v4u& vB, const bool first) {
;     ...
;     const float rl = __builtin_amdgcn_rcpf(o2[0]);
;     LAS unsigned char* stg8 = (LAS unsigned char*)stg;
; #pragma unroll
;     for (int g = 0; g < 4; ++g) {
;         v2u w0, w1; w0.x = cvtpk(o0[4 * g] * rl, o0[4 * g + 1] * rl); w0.y = cvtpk(o0[4 * g + 2] * rl, o0[4 * g + 3] * rl);
;         w1.x = cvtpk(o1[4 * g] * rl, o1[4 * g + 1] * rl); w1.y = cvtpk(o1[4 * g + 2] * rl, o1[4 * g + 3] * rl);
;         *(LAS v2u*)(stg8 + r32 * 144 + (8 * g + 4 * hi) * 2) = w0; *(LAS v2u*)(stg8 + r32 * 144 + (32 + 8 * g + 4 * hi) * 2) = w1;
;     }
;     bf16* Ow = attn + (rowbase + q0 + wid * 32) * CA_PITCH + h * 64;
; #pragma unroll
;     for (int i = 0; i < 4; ++i) { const int row = i * 8 + (lane >> 3), ch = lane & 7; const v4u v = *(const LAS v4u*)(stg8 + row * 144 + ch * 16); *(v4u*)(Ow + (size_t)row * CA_PITCH + ch * 8) = v; }
.LBB0_3755:
	s_nop 8
	v_pk_add_f32 v[48:49], v[48:49], v[50:51]
	s_nop 0
	v_add_f32_e32 v48, v48, v49
	s_nop 0
	v_mov_b32_e32 v49, v48
	s_nop 1
	v_permlane32_swap_b32_e32 v48, v49
	s_nop 1
	v_add_f32_e32 v48, v48, v49
	s_nop 0
	v_rcp_f32_e32 v1, v48
	s_lshl_b64 s[0:1], s[18:19], 11
	v_lshl_add_u64 v[10:11], v[192:193], 0, s[0:1]
	v_mov_b32_e32 v173, v159
	s_waitcnt vmcnt(4)
	v_mul_f32_e32 v2, v1, v16
	v_mul_f32_e32 v3, v1, v17
	v_mul_f32_e32 v4, v1, v18
	v_mul_f32_e32 v5, v1, v19
	v_cvt_pk_bf16_f32 v2, v2, v3
	v_cvt_pk_bf16_f32 v3, v4, v5
	v_mul_f32_e32 v4, v1, v32
	v_mul_f32_e32 v5, v1, v33
	v_cvt_pk_bf16_f32 v4, v4, v5
	v_mul_f32_e32 v5, v1, v34
	v_mul_f32_e32 v6, v1, v35
	v_cvt_pk_bf16_f32 v5, v5, v6
	v_add_u32_e32 v6, 0x10000, v161
	ds_write2_b64 v6, v[2:3], v[4:5] offset1:8
	v_mul_f32_e32 v2, v1, v20
	v_mul_f32_e32 v3, v1, v21
	v_cvt_pk_bf16_f32 v2, v2, v3
	v_mul_f32_e32 v3, v1, v22
	v_mul_f32_e32 v4, v1, v23
	v_cvt_pk_bf16_f32 v3, v3, v4
	v_mul_f32_e32 v4, v1, v36
	v_mul_f32_e32 v5, v1, v37
	v_cvt_pk_bf16_f32 v4, v4, v5
	v_mul_f32_e32 v5, v1, v38
	v_mul_f32_e32 v7, v1, v39
	v_cvt_pk_bf16_f32 v5, v5, v7
	ds_write2_b64 v6, v[2:3], v[4:5] offset0:2 offset1:10
	v_mul_f32_e32 v2, v1, v24
	v_mul_f32_e32 v3, v1, v25
	v_cvt_pk_bf16_f32 v2, v2, v3
	v_mul_f32_e32 v3, v1, v26
	v_mul_f32_e32 v4, v1, v27
	v_cvt_pk_bf16_f32 v3, v3, v4
	v_mul_f32_e32 v4, v1, v40
	v_mul_f32_e32 v5, v1, v41
	v_cvt_pk_bf16_f32 v4, v4, v5
	v_mul_f32_e32 v5, v1, v42
	v_mul_f32_e32 v7, v1, v43
	v_cvt_pk_bf16_f32 v5, v5, v7
	ds_write2_b64 v6, v[2:3], v[4:5] offset0:4 offset1:12
	v_mul_f32_e32 v2, v1, v28
	v_mul_f32_e32 v3, v1, v29
	v_cvt_pk_bf16_f32 v2, v2, v3
	v_mul_f32_e32 v3, v1, v30
	v_mul_f32_e32 v4, v1, v31
	v_cvt_pk_bf16_f32 v3, v3, v4
	v_mul_f32_e32 v4, v1, v44
	v_mul_f32_e32 v5, v1, v45
	v_cvt_pk_bf16_f32 v4, v4, v5
	v_mul_f32_e32 v5, v1, v46
	v_mul_f32_e32 v1, v1, v47
	v_cvt_pk_bf16_f32 v5, v5, v1
	ds_write2_b64 v6, v[2:3], v[4:5] offset0:6 offset1:14
	ds_read_b128 v[2:5], v198 offset:32768
	ds_read_b128 v[6:9], v198 offset:33920
	v_lshl_add_u64 v[12:13], v[10:11], 0, v[172:173]
	v_mov_b32_e32 v175, v159
	v_mov_b32_e32 v177, v159
	s_waitcnt lgkmcnt(1)
	global_store_dwordx4 v[12:13], v[2:5], off
	v_lshl_add_u64 v[12:13], v[10:11], 0, v[174:175]
	ds_read_b128 v[2:5], v198 offset:35072
	s_waitcnt lgkmcnt(1)
	global_store_dwordx4 v[12:13], v[6:9], off
	ds_read_b128 v[6:9], v198 offset:36224
	v_lshl_add_u64 v[12:13], v[10:11], 0, v[176:177]
	v_mov_b32_e32 v179, v159
	s_add_i32 s45, s45, 1
	s_waitcnt lgkmcnt(1)
	global_store_dwordx4 v[12:13], v[2:5], off
	s_cmp_eq_u32 s45, 4
	s_nop 0
	v_lshl_add_u64 v[2:3], v[10:11], 0, v[178:179]
	s_waitcnt lgkmcnt(0)
	global_store_dwordx4 v[2:3], v[6:9], off
	s_cbranch_scc1 .LBB0_3753

; #define LAS __attribute__((address_space(3)))
; __device__ __forceinline__ void attn_unit(const Params& p, LAS unsigned char* lds, int b, int h, int qb, int tid, int wid, int lane, u64& tacc, v4u& kA, v4u& vA, v4u& kB, v4u& vB, const bool first) {
;     ...
;     float m = 0.f; bool started = false; f32x16 o0, o1, o2;
; #pragma unroll
;     for (int i = 0; i < 16; ++i) { o0[i] = 0.f; o1[i] = 0.f; o2[i] = 0.f; }
;     float negv = -1e30f; asm volatile("" : "+v"(negv));
;     const bf16x8 ones8 = (bf16x8){0x3f80, 0x3f80, 0x3f80, 0x3f80, 0x3f80, 0x3f80, 0x3f80, 0x3f80};
;     v4u mwc = *(const v4u*)bmq, mwn = mwc;
;     if (first) {
;         kB = *(const v4u*)ksrc; vB = *(const v4u*)vsrc;
;         kA = *(const v4u*)(ksrc + (size_t)4096); vA = *(const v4u*)(vsrc + (size_t)4096);
;         *(LAS v4u*)(lds + stoff) = kB; *(LAS v4u*)(lds + 8192 + stoff) = vB;
;         kB = *(const v4u*)(ksrc + (size_t)2 * 4096); vB = *(const v4u*)(vsrc + (size_t)2 * 4096);
;     }
;     bf16x8 Eop[2];
; #pragma unroll
;     for (int s = 0; s < 2; ++s) { v4u e; unsigned* ep = (unsigned*)&e;
; #pragma unroll
;         for (int i = 0; i < 4; ++i) { const int k0 = 4 * s + i + 8 * hi; ep[i] = (r32 == k0 ? 0x3F80u : 0u) | (r32 == k0 + 16 ? 0x3F800000u : 0u); }
;         Eop[s] = __builtin_bit_cast(bf16x8, e); }
;     f32x16 nsplat;
; #pragma unroll
;     for (int r = 0; r < 16; ++r) nsplat[r] = -m;
.LBB0_3758:
	v_lshl_add_u64 v[2:3], v[194:195], 0, s[2:3]
	v_lshlrev_b64 v[2:3], 9, v[2:3]
	v_mov_b32_e32 v14, v0
	v_mov_b32_e32 v15, v0
	v_lshl_add_u64 v[196:197], s[6:7], 0, v[2:3]
	v_mov_b32_e32 v1, v0
	v_mov_b32_e32 v2, v0
	v_mov_b32_e32 v3, v0
	v_mov_b32_e32 v4, v0
	v_mov_b32_e32 v5, v0
	v_mov_b32_e32 v6, v0
	v_mov_b32_e32 v7, v0
	v_mov_b32_e32 v8, v0
	v_mov_b32_e32 v9, v0
	v_mov_b32_e32 v10, v0
	v_mov_b32_e32 v11, v0
	v_mov_b32_e32 v12, v0
	v_mov_b32_e32 v13, v0
	v_mov_b32_e32 v30, v159
	v_mov_b32_e32 v31, v159
	v_mov_b64_e32 v[78:79], v[14:15]
	s_lshl_b32 s46, s0, 2
	v_mov_b32_e32 v16, v159
	v_mov_b32_e32 v17, v159
	v_mov_b32_e32 v18, v159
	v_mov_b32_e32 v19, v159
	v_mov_b32_e32 v20, v159
	v_mov_b32_e32 v21, v159
	v_mov_b32_e32 v22, v159
	v_mov_b32_e32 v23, v159
	v_mov_b32_e32 v24, v159
	v_mov_b32_e32 v25, v159
	v_mov_b32_e32 v26, v159
	v_mov_b32_e32 v27, v159
	v_mov_b32_e32 v28, v159
	v_mov_b32_e32 v29, v159
	v_mov_b64_e32 v[46:47], v[30:31]
	v_mov_b64_e32 v[76:77], v[12:13]
	v_mov_b64_e32 v[74:75], v[10:11]
	v_mov_b64_e32 v[72:73], v[8:9]
	v_mov_b64_e32 v[70:71], v[6:7]
	v_mov_b64_e32 v[68:69], v[4:5]
	v_mov_b64_e32 v[66:67], v[2:3]
	v_mov_b64_e32 v[64:65], v[0:1]
	v_mov_b64_e32 v[2:3], v[152:153]
	s_add_i32 s47, s46, s25
	s_add_i32 s48, s46, 4
	s_mov_b32 s51, 0
	s_sub_i32 s49, 0, s46
	s_mov_b64 s[20:21], 0
	v_mov_b32_e32 v171, 0
	v_mov_b64_e32 v[44:45], v[28:29]
	v_mov_b64_e32 v[42:43], v[26:27]
	v_mov_b64_e32 v[40:41], v[24:25]
	v_mov_b64_e32 v[38:39], v[22:23]
	v_mov_b64_e32 v[36:37], v[20:21]
	v_mov_b64_e32 v[34:35], v[18:19]
	v_mov_b64_e32 v[32:33], v[16:17]
	v_mov_b64_e32 v[50:51], v[18:19]
	v_mov_b64_e32 v[48:49], v[16:17]
	v_mov_b64_e32 v[4:5], v[154:155]

.LBB0_3761:
	s_add_i32 s0, s51, 2
	s_sub_i32 s1, s0, s48
	s_min_u32 s2, s0, s1
	s_lshl_b64 s[0:1], s[2:3], 13
	v_lshl_add_u64 v[6:7], v[180:181], 0, s[0:1]
	v_lshl_add_u64 v[8:9], v[182:183], 0, s[0:1]
	s_mov_b32 m0, s70
	s_nop 0
	global_load_lds_dwordx4 v[6:7], off
	s_add_i32 m0, s70, 0x2000
	s_nop 0
	global_load_lds_dwordx4 v[8:9], off
	s_add_i32 s0, s51, 3
	s_sub_i32 s1, s0, s48
	s_min_u32 s2, s0, s1
	s_lshl_b64 s[0:1], s[2:3], 13
	v_lshl_add_u64 v[6:7], v[180:181], 0, s[0:1]
	v_lshl_add_u64 v[8:9], v[182:183], 0, s[0:1]
	s_add_i32 m0, s70, 0x4000
	s_nop 0
	global_load_lds_dwordx4 v[6:7], off
	s_add_i32 m0, s70, 0x6000
	s_nop 0
	global_load_lds_dwordx4 v[8:9], off
	s_cmp_gt_u32 s51, s47
	s_cbranch_scc1 .LBB0_3765
	ds_read_b128 v[6:9], v200
	ds_read_b128 v[10:13], v200 offset:512
	v_lshrrev_b32_e32 v1, v160, v152
	v_lshrrev_b32_e32 v14, v160, v153
	v_bitop3_b32 v228, v1, s27, v1 bitop3:0xc
	v_bitop3_b32 v229, v1, s28, v1 bitop3:0xc
	v_bitop3_b32 v230, v1, s29, v1 bitop3:0xc
	v_bitop3_b32 v231, v1, s30, v1 bitop3:0xc
	s_waitcnt lgkmcnt(1)
	v_mfma_f32_32x32x16_bf16 v[80:95], v[6:9], v[144:147], v[64:79]
	v_mul_u32_u24_e32 v228, 0xf000, v228
	v_mul_u32_u24_e32 v229, 0x7800, v229
	v_mul_u32_u24_e32 v230, 0x3c00, v230
	v_mul_u32_u24_e32 v231, 0x1e00, v231
	s_waitcnt lgkmcnt(0)
	v_mfma_f32_32x32x16_bf16 v[96:111], v[10:13], v[144:147], v[64:79]
	ds_read_b128 v[6:9], v200 offset:2048
	ds_read_b128 v[10:13], v200 offset:2560
	v_bitop3_b32 v232, v14, s27, v14 bitop3:0xc
	v_bitop3_b32 v233, v14, s28, v14 bitop3:0xc
	v_bitop3_b32 v234, v14, s29, v14 bitop3:0xc
	v_bitop3_b32 v235, v14, s30, v14 bitop3:0xc
	v_mul_u32_u24_e32 v232, 0xf000, v232
	v_mul_u32_u24_e32 v233, 0x7800, v233
	v_mul_u32_u24_e32 v234, 0x3c00, v234
	v_mul_u32_u24_e32 v235, 0x1e00, v235
	s_waitcnt lgkmcnt(1)
	v_mfma_f32_32x32x16_bf16 v[80:95], v[6:9], v[136:139], v[80:95]
	v_bitop3_b32 v236, v1, s31, v1 bitop3:0xc
	v_bitop3_b32 v237, v1, s33, v1 bitop3:0xc
	v_bitop3_b32 v238, v1, s34, v1 bitop3:0xc
	v_bitop3_b32 v239, v1, s35, v1 bitop3:0xc
	s_waitcnt lgkmcnt(0)
	v_mfma_f32_32x32x16_bf16 v[96:111], v[10:13], v[136:139], v[96:111]
	ds_read_b128 v[6:9], v200 offset:4096
	ds_read_b128 v[10:13], v200 offset:4608
	v_mul_u32_u24_e32 v236, 0xf00, v236
	v_mul_u32_u24_e32 v237, 0x780, v237
	v_mul_u32_u24_e32 v238, 0x3c0, v238
	v_mul_u32_u24_e32 v239, 0x1e0, v239
	v_bitop3_b32 v224, v14, s31, v14 bitop3:0xc
	v_bitop3_b32 v225, v14, s33, v14 bitop3:0xc
	v_bitop3_b32 v226, v14, s34, v14 bitop3:0xc
	v_bitop3_b32 v227, v14, s35, v14 bitop3:0xc
	s_waitcnt lgkmcnt(1)
	v_mfma_f32_32x32x16_bf16 v[80:95], v[6:9], v[140:143], v[80:95]
	v_mul_u32_u24_e32 v224, 0xf00, v224
	v_mul_u32_u24_e32 v225, 0x780, v225
	v_mul_u32_u24_e32 v226, 0x3c0, v226
	v_mul_u32_u24_e32 v227, 0x1e0, v227
	s_waitcnt lgkmcnt(0)
	v_mfma_f32_32x32x16_bf16 v[96:111], v[10:13], v[140:143], v[96:111]
	ds_read_b128 v[6:9], v200 offset:6144
	ds_read_b128 v[10:13], v200 offset:6656
	s_xor_b64 s[4:5], s[20:21], -1
	s_waitcnt lgkmcnt(1)
	v_mfma_f32_32x32x16_bf16 v[80:95], v[6:9], v[148:151], v[80:95]
	s_waitcnt lgkmcnt(0)
	v_mfma_f32_32x32x16_bf16 v[96:111], v[10:13], v[148:151], v[96:111]
	v_mfma_f32_32x32x16_bf16 v[80:95], v[112:115], v[228:231], v[80:95]
	v_mfma_f32_32x32x16_bf16 v[96:111], v[112:115], v[232:235], v[96:111]
	v_mfma_f32_32x32x16_bf16 v[80:95], v[116:119], v[236:239], v[80:95]
	v_mfma_f32_32x32x16_bf16 v[96:111], v[116:119], v[224:227], v[96:111]
	s_nop 15
	s_nop 7
	v_max3_f32 v1, v80, v81, v82
	v_max3_f32 v6, v83, v84, v85
	v_max3_f32 v1, v1, v86, v87
	v_max3_f32 v6, v6, v88, v89
	v_max3_f32 v1, v1, v90, v91
	v_max3_f32 v6, v6, v92, v93
	v_max3_f32 v1, v1, v94, v95
	v_max_f32 v1, v1, v6
	s_nop 0
	v_max3_f32 v7, v96, v97, v98
	v_max3_f32 v6, v99, v100, v101
	v_max3_f32 v7, v7, v102, v103
	v_max3_f32 v6, v6, v104, v105
	v_max3_f32 v7, v7, v106, v107
	v_max3_f32 v6, v6, v108, v109
	v_max3_f32 v7, v7, v110, v111
	v_max3_f32 v7, v7, v6, v1
	s_nop 0
	v_mov_b32_e32 v1, v7
	s_nop 1
	v_permlane32_swap_b32_e32 v7, v1
	v_max_f32_e32 v1, v1, v1
	v_max_f32_e32 v6, v7, v7
	v_max_f32_e32 v1, v6, v1
	v_cmp_lt_f32_e64 s[0:1], s36, v1
	s_and_b64 s[10:11], s[0:1], s[4:5]
	v_cmp_lt_f32_e32 vcc, s37, v1
	s_or_b64 s[4:5], vcc, s[10:11]
	v_cndmask_b32_e64 v6, 0, 1, s[4:5]
	v_cmp_ne_u32_e32 vcc, 0, v6
	s_cbranch_vccz .LBB0_3764
	v_cndmask_b32_e64 v6, 0, v1, s[4:5]
	v_exp_f32_e64 v1, -v6
	v_add_f32_e32 v171, v171, v6
	s_or_b64 s[0:1], s[20:21], s[0:1]
	v_xor_b32_e32 v64, 0x80000000, v171
	v_cndmask_b32_e64 v8, v1, 1.0, s[10:11]
	s_andn2_b64 s[4:5], s[20:21], exec
	s_and_b64 s[0:1], s[0:1], exec
	v_pk_add_f32 v[80:81], v[80:81], v[6:7] op_sel_hi:[1,0] neg_lo:[0,1] neg_hi:[0,1]
	v_pk_add_f32 v[96:97], v[96:97], v[6:7] op_sel_hi:[1,0] neg_lo:[0,1] neg_hi:[0,1]
	v_pk_add_f32 v[82:83], v[82:83], v[6:7] op_sel_hi:[1,0] neg_lo:[0,1] neg_hi:[0,1]
	v_pk_add_f32 v[98:99], v[98:99], v[6:7] op_sel_hi:[1,0] neg_lo:[0,1] neg_hi:[0,1]
	v_pk_add_f32 v[84:85], v[84:85], v[6:7] op_sel_hi:[1,0] neg_lo:[0,1] neg_hi:[0,1]
	v_pk_add_f32 v[100:101], v[100:101], v[6:7] op_sel_hi:[1,0] neg_lo:[0,1] neg_hi:[0,1]
	v_pk_add_f32 v[86:87], v[86:87], v[6:7] op_sel_hi:[1,0] neg_lo:[0,1] neg_hi:[0,1]
	v_pk_add_f32 v[102:103], v[102:103], v[6:7] op_sel_hi:[1,0] neg_lo:[0,1] neg_hi:[0,1]
	v_pk_add_f32 v[88:89], v[88:89], v[6:7] op_sel_hi:[1,0] neg_lo:[0,1] neg_hi:[0,1]
	v_pk_add_f32 v[104:105], v[104:105], v[6:7] op_sel_hi:[1,0] neg_lo:[0,1] neg_hi:[0,1]
	v_pk_add_f32 v[90:91], v[90:91], v[6:7] op_sel_hi:[1,0] neg_lo:[0,1] neg_hi:[0,1]
	v_pk_add_f32 v[106:107], v[106:107], v[6:7] op_sel_hi:[1,0] neg_lo:[0,1] neg_hi:[0,1]
	v_pk_add_f32 v[92:93], v[92:93], v[6:7] op_sel_hi:[1,0] neg_lo:[0,1] neg_hi:[0,1]
	v_pk_add_f32 v[108:109], v[108:109], v[6:7] op_sel_hi:[1,0] neg_lo:[0,1] neg_hi:[0,1]
	v_pk_add_f32 v[94:95], v[94:95], v[6:7] op_sel_hi:[1,0] neg_lo:[0,1] neg_hi:[0,1]
	v_pk_add_f32 v[110:111], v[110:111], v[6:7] op_sel_hi:[1,0] neg_lo:[0,1] neg_hi:[0,1]
	v_mov_b32_e32 v65, v64
	v_mov_b32_e32 v66, v64
	v_mov_b32_e32 v67, v64
	v_mov_b32_e32 v68, v64
	v_mov_b32_e32 v69, v64
	v_mov_b32_e32 v70, v64
	v_mov_b32_e32 v71, v64
	v_mov_b32_e32 v72, v64
	v_mov_b32_e32 v73, v64
	v_mov_b32_e32 v74, v64
	v_mov_b32_e32 v75, v64
	v_mov_b32_e32 v76, v64
	v_mov_b32_e32 v77, v64
	v_mov_b32_e32 v78, v64
	v_mov_b32_e32 v79, v64
	v_pk_mul_f32 v[30:31], v[30:31], v[8:9] op_sel_hi:[1,0]
	v_pk_mul_f32 v[28:29], v[28:29], v[8:9] op_sel_hi:[1,0]
	v_pk_mul_f32 v[26:27], v[26:27], v[8:9] op_sel_hi:[1,0]
	v_pk_mul_f32 v[24:25], v[24:25], v[8:9] op_sel_hi:[1,0]
	v_pk_mul_f32 v[22:23], v[22:23], v[8:9] op_sel_hi:[1,0]
	v_pk_mul_f32 v[20:21], v[20:21], v[8:9] op_sel_hi:[1,0]
	v_pk_mul_f32 v[18:19], v[18:19], v[8:9] op_sel_hi:[1,0]
	v_pk_mul_f32 v[16:17], v[16:17], v[8:9] op_sel_hi:[1,0]
	v_pk_mul_f32 v[46:47], v[46:47], v[8:9] op_sel_hi:[1,0]
	v_pk_mul_f32 v[44:45], v[44:45], v[8:9] op_sel_hi:[1,0]
	v_pk_mul_f32 v[42:43], v[42:43], v[8:9] op_sel_hi:[1,0]
	v_pk_mul_f32 v[40:41], v[40:41], v[8:9] op_sel_hi:[1,0]
	v_pk_mul_f32 v[38:39], v[38:39], v[8:9] op_sel_hi:[1,0]
	v_pk_mul_f32 v[36:37], v[36:37], v[8:9] op_sel_hi:[1,0]
	v_pk_mul_f32 v[34:35], v[34:35], v[8:9] op_sel_hi:[1,0]
	v_pk_mul_f32 v[32:33], v[32:33], v[8:9] op_sel_hi:[1,0]
	v_pk_mul_f32 v[50:51], v[50:51], v[8:9] op_sel_hi:[1,0]
	v_pk_mul_f32 v[48:49], v[48:49], v[8:9] op_sel_hi:[1,0]
	s_or_b64 s[20:21], s[4:5], s[0:1]
.LBB0_3764:
	v_add_u32_e32 v1, 0, v157
	ds_read_b64_tr_b16 v[202:203], v1 offset:8192
	ds_read_b64_tr_b16 v[204:205], v1 offset:8704
	ds_read_b64_tr_b16 v[206:207], v1 offset:12288
	ds_read_b64_tr_b16 v[208:209], v1 offset:12800
	v_exp_f32_e32 v80, v80
	v_exp_f32_e32 v81, v81
	v_exp_f32_e32 v82, v82
	v_exp_f32_e32 v83, v83
	v_exp_f32_e32 v84, v84
	v_exp_f32_e32 v85, v85
	v_exp_f32_e32 v86, v86
	v_exp_f32_e32 v87, v87
	v_cvt_pk_bf16_f32 v6, v80, v81
	v_cvt_pk_bf16_f32 v7, v82, v83
	v_cvt_pk_bf16_f32 v8, v84, v85
	v_cvt_pk_bf16_f32 v9, v86, v87
	v_pk_add_f32 v[48:49], v[48:49], v[80:81]
	v_pk_add_f32 v[50:51], v[50:51], v[82:83]
	v_pk_add_f32 v[48:49], v[48:49], v[84:85]
	v_pk_add_f32 v[50:51], v[50:51], v[86:87]
	ds_read_b64_tr_b16 v[210:211], v1 offset:9216
	ds_read_b64_tr_b16 v[212:213], v1 offset:9728
	ds_read_b64_tr_b16 v[214:215], v1 offset:13312
	ds_read_b64_tr_b16 v[216:217], v1 offset:13824
	s_waitcnt lgkmcnt(4)
	v_mfma_f32_32x32x16_bf16 v[16:31], v[202:205], v[6:9], v[16:31]
	v_exp_f32_e32 v88, v88
	v_exp_f32_e32 v89, v89
	v_exp_f32_e32 v90, v90
	v_mfma_f32_32x32x16_bf16 v[32:47], v[206:209], v[6:9], v[32:47]
	v_exp_f32_e32 v91, v91
	v_exp_f32_e32 v92, v92
	v_exp_f32_e32 v93, v93
	v_exp_f32_e32 v94, v94
	v_exp_f32_e32 v95, v95
	v_cvt_pk_bf16_f32 v10, v88, v89
	v_cvt_pk_bf16_f32 v11, v90, v91
	v_cvt_pk_bf16_f32 v12, v92, v93
	v_cvt_pk_bf16_f32 v13, v94, v95
	v_pk_add_f32 v[48:49], v[48:49], v[88:89]
	v_pk_add_f32 v[50:51], v[50:51], v[90:91]
	v_pk_add_f32 v[48:49], v[48:49], v[92:93]
	v_pk_add_f32 v[50:51], v[50:51], v[94:95]
	ds_read_b64_tr_b16 v[202:203], v1 offset:10240
	ds_read_b64_tr_b16 v[204:205], v1 offset:10752
	ds_read_b64_tr_b16 v[206:207], v1 offset:14336
	ds_read_b64_tr_b16 v[208:209], v1 offset:14848
	s_waitcnt lgkmcnt(4)
	v_mfma_f32_32x32x16_bf16 v[16:31], v[210:213], v[10:13], v[16:31]
	v_exp_f32_e32 v96, v96
	v_exp_f32_e32 v97, v97
	v_exp_f32_e32 v98, v98
	v_mfma_f32_32x32x16_bf16 v[32:47], v[214:217], v[10:13], v[32:47]
	v_exp_f32_e32 v99, v99
	v_exp_f32_e32 v100, v100
	v_exp_f32_e32 v101, v101
	v_exp_f32_e32 v102, v102
	v_exp_f32_e32 v103, v103
	v_cvt_pk_bf16_f32 v228, v96, v97
	v_cvt_pk_bf16_f32 v229, v98, v99
	v_cvt_pk_bf16_f32 v230, v100, v101
	v_cvt_pk_bf16_f32 v231, v102, v103
	v_pk_add_f32 v[48:49], v[48:49], v[96:97]
	v_pk_add_f32 v[50:51], v[50:51], v[98:99]
	v_pk_add_f32 v[48:49], v[48:49], v[100:101]
	v_pk_add_f32 v[50:51], v[50:51], v[102:103]
	ds_read_b64_tr_b16 v[210:211], v1 offset:11264
	ds_read_b64_tr_b16 v[212:213], v1 offset:11776
	ds_read_b64_tr_b16 v[214:215], v1 offset:15360
	ds_read_b64_tr_b16 v[216:217], v1 offset:15872
	s_waitcnt lgkmcnt(4)
	v_mfma_f32_32x32x16_bf16 v[16:31], v[202:205], v[228:231], v[16:31]
	v_exp_f32_e32 v104, v104
	v_exp_f32_e32 v105, v105
	v_exp_f32_e32 v106, v106
	v_mfma_f32_32x32x16_bf16 v[32:47], v[206:209], v[228:231], v[32:47]
	v_exp_f32_e32 v107, v107
	v_exp_f32_e32 v108, v108
	v_exp_f32_e32 v109, v109
	v_exp_f32_e32 v110, v110
	v_exp_f32_e32 v111, v111
	v_cvt_pk_bf16_f32 v232, v104, v105
	v_cvt_pk_bf16_f32 v233, v106, v107
	v_cvt_pk_bf16_f32 v234, v108, v109
	v_cvt_pk_bf16_f32 v235, v110, v111
	v_pk_add_f32 v[48:49], v[48:49], v[104:105]
	v_pk_add_f32 v[50:51], v[50:51], v[106:107]
	v_pk_add_f32 v[48:49], v[48:49], v[108:109]
	v_pk_add_f32 v[50:51], v[50:51], v[110:111]
	s_waitcnt lgkmcnt(0)
	s_nop 0
	v_mfma_f32_32x32x16_bf16 v[16:31], v[210:213], v[232:235], v[16:31]
	v_mfma_f32_32x32x16_bf16 v[32:47], v[214:217], v[232:235], v[32:47]
.LBB0_3765:
	s_cmp_ge_u32 s51, s47
	s_cbranch_scc1 .LBB0_3770
	ds_read_b128 v[6:9], v200 offset:16384
	ds_read_b128 v[10:13], v200 offset:16896
	v_lshrrev_b32_e32 v1, v160, v154
	v_lshrrev_b32_e32 v14, v160, v155
	v_bitop3_b32 v228, v1, s27, v1 bitop3:0xc
	v_bitop3_b32 v229, v1, s28, v1 bitop3:0xc
	v_bitop3_b32 v230, v1, s29, v1 bitop3:0xc
	v_bitop3_b32 v231, v1, s30, v1 bitop3:0xc
	s_waitcnt lgkmcnt(1)
	v_mfma_f32_32x32x16_bf16 v[80:95], v[6:9], v[144:147], v[64:79]
	v_mul_u32_u24_e32 v228, 0xf000, v228
	v_mul_u32_u24_e32 v229, 0x7800, v229
	v_mul_u32_u24_e32 v230, 0x3c00, v230
	v_mul_u32_u24_e32 v231, 0x1e00, v231
	s_waitcnt lgkmcnt(0)
	v_mfma_f32_32x32x16_bf16 v[96:111], v[10:13], v[144:147], v[64:79]
	ds_read_b128 v[6:9], v200 offset:18432
	ds_read_b128 v[10:13], v200 offset:18944
	v_bitop3_b32 v232, v14, s27, v14 bitop3:0xc
	v_bitop3_b32 v233, v14, s28, v14 bitop3:0xc
	v_bitop3_b32 v234, v14, s29, v14 bitop3:0xc
	v_bitop3_b32 v235, v14, s30, v14 bitop3:0xc
	v_mul_u32_u24_e32 v232, 0xf000, v232
	v_mul_u32_u24_e32 v233, 0x7800, v233
	v_mul_u32_u24_e32 v234, 0x3c00, v234
	v_mul_u32_u24_e32 v235, 0x1e00, v235
	s_waitcnt lgkmcnt(1)
	v_mfma_f32_32x32x16_bf16 v[80:95], v[6:9], v[136:139], v[80:95]
	v_bitop3_b32 v236, v1, s31, v1 bitop3:0xc
	v_bitop3_b32 v237, v1, s33, v1 bitop3:0xc
	v_bitop3_b32 v238, v1, s34, v1 bitop3:0xc
	v_bitop3_b32 v239, v1, s35, v1 bitop3:0xc
	s_waitcnt lgkmcnt(0)
	v_mfma_f32_32x32x16_bf16 v[96:111], v[10:13], v[136:139], v[96:111]
	ds_read_b128 v[6:9], v200 offset:20480
	ds_read_b128 v[10:13], v200 offset:20992
	v_mul_u32_u24_e32 v236, 0xf00, v236
	v_mul_u32_u24_e32 v237, 0x780, v237
	v_mul_u32_u24_e32 v238, 0x3c0, v238
	v_mul_u32_u24_e32 v239, 0x1e0, v239
	v_bitop3_b32 v224, v14, s31, v14 bitop3:0xc
	v_bitop3_b32 v225, v14, s33, v14 bitop3:0xc
	v_bitop3_b32 v226, v14, s34, v14 bitop3:0xc
	v_bitop3_b32 v227, v14, s35, v14 bitop3:0xc
	s_waitcnt lgkmcnt(1)
	v_mfma_f32_32x32x16_bf16 v[80:95], v[6:9], v[140:143], v[80:95]
	v_mul_u32_u24_e32 v224, 0xf00, v224
	v_mul_u32_u24_e32 v225, 0x780, v225
	v_mul_u32_u24_e32 v226, 0x3c0, v226
	v_mul_u32_u24_e32 v227, 0x1e0, v227
	s_waitcnt lgkmcnt(0)
	v_mfma_f32_32x32x16_bf16 v[96:111], v[10:13], v[140:143], v[96:111]
	ds_read_b128 v[6:9], v200 offset:22528
	ds_read_b128 v[10:13], v200 offset:23040
	s_xor_b64 s[4:5], s[20:21], -1
	v_cndmask_b32_e64 v1, 0, 1, s[4:5]
	v_cmp_ne_u32_e32 vcc, 0, v1
	s_waitcnt lgkmcnt(1)
	v_mfma_f32_32x32x16_bf16 v[80:95], v[6:9], v[148:151], v[80:95]
	s_waitcnt lgkmcnt(0)
	v_mfma_f32_32x32x16_bf16 v[96:111], v[10:13], v[148:151], v[96:111]
	v_mfma_f32_32x32x16_bf16 v[80:95], v[112:115], v[228:231], v[80:95]
	v_mfma_f32_32x32x16_bf16 v[96:111], v[112:115], v[232:235], v[96:111]
	v_mfma_f32_32x32x16_bf16 v[80:95], v[116:119], v[236:239], v[80:95]
	v_mfma_f32_32x32x16_bf16 v[96:111], v[116:119], v[224:227], v[96:111]
	s_cbranch_vccz .LBB0_3769
	s_nop 15
	s_nop 7
	v_max3_f32 v1, v80, v81, v82
	v_max3_f32 v6, v83, v84, v85
	v_max3_f32 v1, v1, v86, v87
	v_max3_f32 v6, v6, v88, v89
	v_max3_f32 v1, v1, v90, v91
	v_max3_f32 v6, v6, v92, v93
	v_max3_f32 v1, v1, v94, v95
	v_max_f32 v1, v1, v6
	s_nop 0
	v_max3_f32 v7, v96, v97, v98
	v_max3_f32 v6, v99, v100, v101
	v_max3_f32 v7, v7, v102, v103
	v_max3_f32 v6, v6, v104, v105
	v_max3_f32 v7, v7, v106, v107
	v_max3_f32 v6, v6, v108, v109
	v_max3_f32 v7, v7, v110, v111
	v_max3_f32 v7, v7, v6, v1
	s_nop 0
	v_mov_b32_e32 v1, v7
	s_nop 1
	v_permlane32_swap_b32_e32 v7, v1
	v_max_f32_e32 v1, v1, v1
	v_max_f32_e32 v6, v7, v7
	v_max_f32_e32 v1, v6, v1
	v_cmp_lt_f32_e64 s[0:1], s36, v1
	s_and_b64 s[10:11], s[0:1], s[4:5]
	v_cmp_lt_f32_e32 vcc, s37, v1
	s_or_b64 s[4:5], vcc, s[10:11]
	v_cndmask_b32_e64 v6, 0, 1, s[4:5]
	v_cmp_ne_u32_e32 vcc, 0, v6
	s_cbranch_vccz .LBB0_3769
	v_cndmask_b32_e64 v1, 0, v1, s[4:5]
	v_exp_f32_e64 v6, -v1
	v_add_f32_e32 v171, v171, v1
	s_or_b64 s[0:1], s[20:21], s[0:1]
	v_xor_b32_e32 v64, 0x80000000, v171
	v_cndmask_b32_e64 v6, v6, 1.0, s[10:11]
	s_andn2_b64 s[4:5], s[20:21], exec
	s_and_b64 s[0:1], s[0:1], exec
	v_mov_b32_e32 v65, v64
	v_mov_b32_e32 v66, v64
	v_mov_b32_e32 v67, v64
	v_mov_b32_e32 v68, v64
	v_mov_b32_e32 v69, v64
	v_mov_b32_e32 v70, v64
	v_mov_b32_e32 v71, v64
	v_mov_b32_e32 v72, v64
	v_mov_b32_e32 v73, v64
	v_mov_b32_e32 v74, v64
	v_mov_b32_e32 v75, v64
	v_mov_b32_e32 v76, v64
	v_mov_b32_e32 v77, v64
	v_mov_b32_e32 v78, v64
	v_mov_b32_e32 v79, v64
	v_pk_mul_f32 v[30:31], v[30:31], v[6:7] op_sel_hi:[1,0]
	v_pk_mul_f32 v[28:29], v[28:29], v[6:7] op_sel_hi:[1,0]
	v_pk_mul_f32 v[26:27], v[26:27], v[6:7] op_sel_hi:[1,0]
	v_pk_mul_f32 v[24:25], v[24:25], v[6:7] op_sel_hi:[1,0]
	v_pk_mul_f32 v[22:23], v[22:23], v[6:7] op_sel_hi:[1,0]
	v_pk_mul_f32 v[20:21], v[20:21], v[6:7] op_sel_hi:[1,0]
	v_pk_mul_f32 v[18:19], v[18:19], v[6:7] op_sel_hi:[1,0]
	v_pk_mul_f32 v[16:17], v[16:17], v[6:7] op_sel_hi:[1,0]
	v_pk_mul_f32 v[46:47], v[46:47], v[6:7] op_sel_hi:[1,0]
	v_pk_mul_f32 v[44:45], v[44:45], v[6:7] op_sel_hi:[1,0]
	v_pk_mul_f32 v[42:43], v[42:43], v[6:7] op_sel_hi:[1,0]
	v_pk_mul_f32 v[40:41], v[40:41], v[6:7] op_sel_hi:[1,0]
	v_pk_mul_f32 v[38:39], v[38:39], v[6:7] op_sel_hi:[1,0]
	v_pk_mul_f32 v[36:37], v[36:37], v[6:7] op_sel_hi:[1,0]
	v_pk_mul_f32 v[34:35], v[34:35], v[6:7] op_sel_hi:[1,0]
	v_pk_mul_f32 v[32:33], v[32:33], v[6:7] op_sel_hi:[1,0]
	v_pk_mul_f32 v[50:51], v[50:51], v[6:7] op_sel_hi:[1,0]
	v_pk_mul_f32 v[48:49], v[48:49], v[6:7] op_sel_hi:[1,0]
	v_sub_f32_e32 v95, v95, v1
	v_sub_f32_e32 v94, v94, v1
	v_sub_f32_e32 v93, v93, v1
	v_sub_f32_e32 v92, v92, v1
	v_sub_f32_e32 v91, v91, v1
	v_sub_f32_e32 v90, v90, v1
	v_sub_f32_e32 v89, v89, v1
	v_sub_f32_e32 v88, v88, v1
	v_sub_f32_e32 v87, v87, v1
	v_sub_f32_e32 v86, v86, v1
	v_sub_f32_e32 v85, v85, v1
	v_sub_f32_e32 v84, v84, v1
	v_sub_f32_e32 v83, v83, v1
	v_sub_f32_e32 v82, v82, v1
	v_sub_f32_e32 v81, v81, v1
	v_sub_f32_e32 v80, v80, v1
	v_sub_f32_e32 v111, v111, v1
	v_sub_f32_e32 v110, v110, v1
	v_sub_f32_e32 v109, v109, v1
	v_sub_f32_e32 v108, v108, v1
	v_sub_f32_e32 v107, v107, v1
	v_sub_f32_e32 v106, v106, v1
	v_sub_f32_e32 v105, v105, v1
	v_sub_f32_e32 v104, v104, v1
	v_sub_f32_e32 v103, v103, v1
	v_sub_f32_e32 v102, v102, v1
	v_sub_f32_e32 v101, v101, v1
	v_sub_f32_e32 v100, v100, v1
	v_sub_f32_e32 v99, v99, v1
	v_sub_f32_e32 v98, v98, v1
	v_sub_f32_e32 v97, v97, v1
	v_sub_f32_e32 v96, v96, v1
	s_or_b64 s[20:21], s[4:5], s[0:1]
.LBB0_3769:
	s_nop 8
	v_add_u32_e32 v1, 0, v157
	ds_read_b64_tr_b16 v[202:203], v1 offset:24576
	ds_read_b64_tr_b16 v[204:205], v1 offset:25088
	ds_read_b64_tr_b16 v[206:207], v1 offset:28672
	ds_read_b64_tr_b16 v[208:209], v1 offset:29184
	v_exp_f32_e32 v80, v80
	v_exp_f32_e32 v81, v81
	v_exp_f32_e32 v82, v82
	v_exp_f32_e32 v83, v83
	v_exp_f32_e32 v84, v84
	v_exp_f32_e32 v85, v85
	v_exp_f32_e32 v86, v86
	v_exp_f32_e32 v87, v87
	v_cvt_pk_bf16_f32 v6, v80, v81
	v_cvt_pk_bf16_f32 v7, v82, v83
	v_cvt_pk_bf16_f32 v8, v84, v85
	v_cvt_pk_bf16_f32 v9, v86, v87
	v_pk_add_f32 v[48:49], v[48:49], v[80:81]
	v_pk_add_f32 v[50:51], v[50:51], v[82:83]
	v_pk_add_f32 v[48:49], v[48:49], v[84:85]
	v_pk_add_f32 v[50:51], v[50:51], v[86:87]
	ds_read_b64_tr_b16 v[210:211], v1 offset:25600
	ds_read_b64_tr_b16 v[212:213], v1 offset:26112
	ds_read_b64_tr_b16 v[214:215], v1 offset:29696
	ds_read_b64_tr_b16 v[216:217], v1 offset:30208
	s_waitcnt lgkmcnt(4)
	v_mfma_f32_32x32x16_bf16 v[16:31], v[202:205], v[6:9], v[16:31]
	v_exp_f32_e32 v88, v88
	v_exp_f32_e32 v89, v89
	v_exp_f32_e32 v90, v90
	v_mfma_f32_32x32x16_bf16 v[32:47], v[206:209], v[6:9], v[32:47]
	v_exp_f32_e32 v91, v91
	v_exp_f32_e32 v92, v92
	v_exp_f32_e32 v93, v93
	v_exp_f32_e32 v94, v94
	v_exp_f32_e32 v95, v95
	v_cvt_pk_bf16_f32 v10, v88, v89
	v_cvt_pk_bf16_f32 v11, v90, v91
	v_cvt_pk_bf16_f32 v12, v92, v93
	v_cvt_pk_bf16_f32 v13, v94, v95
	v_pk_add_f32 v[48:49], v[48:49], v[88:89]
	v_pk_add_f32 v[50:51], v[50:51], v[90:91]
	v_pk_add_f32 v[48:49], v[48:49], v[92:93]
	v_pk_add_f32 v[50:51], v[50:51], v[94:95]
	ds_read_b64_tr_b16 v[202:203], v1 offset:26624
	ds_read_b64_tr_b16 v[204:205], v1 offset:27136
	ds_read_b64_tr_b16 v[206:207], v1 offset:30720
	ds_read_b64_tr_b16 v[208:209], v1 offset:31232
	s_waitcnt lgkmcnt(4)
	v_mfma_f32_32x32x16_bf16 v[16:31], v[210:213], v[10:13], v[16:31]
	v_exp_f32_e32 v96, v96
	v_exp_f32_e32 v97, v97
	v_exp_f32_e32 v98, v98
	v_mfma_f32_32x32x16_bf16 v[32:47], v[214:217], v[10:13], v[32:47]
	v_exp_f32_e32 v99, v99
	v_exp_f32_e32 v100, v100
	v_exp_f32_e32 v101, v101
	v_exp_f32_e32 v102, v102
	v_exp_f32_e32 v103, v103
	v_cvt_pk_bf16_f32 v228, v96, v97
	v_cvt_pk_bf16_f32 v229, v98, v99
	v_cvt_pk_bf16_f32 v230, v100, v101
	v_cvt_pk_bf16_f32 v231, v102, v103
	v_pk_add_f32 v[48:49], v[48:49], v[96:97]
	v_pk_add_f32 v[50:51], v[50:51], v[98:99]
	v_pk_add_f32 v[48:49], v[48:49], v[100:101]
	v_pk_add_f32 v[50:51], v[50:51], v[102:103]
	ds_read_b64_tr_b16 v[210:211], v1 offset:27648
	ds_read_b64_tr_b16 v[212:213], v1 offset:28160
	ds_read_b64_tr_b16 v[214:215], v1 offset:31744
	ds_read_b64_tr_b16 v[216:217], v1 offset:32256
	s_waitcnt lgkmcnt(4)
	v_mfma_f32_32x32x16_bf16 v[16:31], v[202:205], v[228:231], v[16:31]
	v_exp_f32_e32 v104, v104
	v_exp_f32_e32 v105, v105
	v_exp_f32_e32 v106, v106
	v_mfma_f32_32x32x16_bf16 v[32:47], v[206:209], v[228:231], v[32:47]
	v_exp_f32_e32 v107, v107
	v_exp_f32_e32 v108, v108
	v_exp_f32_e32 v109, v109
	v_exp_f32_e32 v110, v110
	v_exp_f32_e32 v111, v111
	v_cvt_pk_bf16_f32 v232, v104, v105
	v_cvt_pk_bf16_f32 v233, v106, v107
	v_cvt_pk_bf16_f32 v234, v108, v109
	v_cvt_pk_bf16_f32 v235, v110, v111
	v_pk_add_f32 v[48:49], v[48:49], v[104:105]
	v_pk_add_f32 v[50:51], v[50:51], v[106:107]
	v_pk_add_f32 v[48:49], v[48:49], v[108:109]
	v_pk_add_f32 v[50:51], v[50:51], v[110:111]
	s_waitcnt lgkmcnt(0)
	s_nop 0
	v_mfma_f32_32x32x16_bf16 v[16:31], v[210:213], v[232:235], v[16:31]
	v_mfma_f32_32x32x16_bf16 v[32:47], v[214:217], v[232:235], v[32:47]

;     __device__ bool next(int i, Unit& u) const { if (i != 0) return false; return so.next(round, u); }
;     __device__ __forceinline__ bool next(int i, Unit& u) const { if (i > 0 || !on) return false; u.pm = pm; u.pn = 0; return true; }
; template <class Epi, class Sched, bool ALIGN_EPI = false, bool SP2 = false, bool MIDHOOK = false>
; __device__ __forceinline__ void gemm_phase(PG8_LAS unsigned char* lds, const Gemm g, const Sched& S, const Epi& E) {
;     ...
;         const bool has_next = S.next(ui + 1, nxt);
;         const char* nA = has_next ? (const char*)g.A + (size_t)nxt.pm * tstep : cA; const char* nB = has_next ? (const char*)g.Bt + (size_t)nxt.pn * tstep : cB;
;         for (int t = 0; t < nt; t += 2) {
;             if constexpr (MIDHOOK) { if (t == nt / 2) E.mid(acc, cur, wr, wc, fr, fq); }
;             const bool last = (t == nt - 2);
;             const char* a1 = cA + (size_t)(t + 1) * kstep;
;             const char* a2 = last ? nA : cA + (size_t)(t + 2) * kstep; const char* b2 = last ? nB : cB + (size_t)(t + 2) * kstep;
;     ...
; #pragma unroll
;         for (int a = 0; a < 2; ++a)
; #pragma unroll
;             for (int b = 0; b < 2; ++b)
; #pragma unroll
;                 for (int m = 0; m < 4; ++m)
; #pragma unroll
;                     for (int n = 0; n < 2; ++n) acc[a][b][m][n] = (f32x4){0.f, 0.f, 0.f, 0.f};
;         cur = nxt; cA = nA; cB = nB; ++ui;
.LBB0_3840:
	s_ashr_i32 s19, s18, 31
	s_lshl_b64 s[20:21], s[18:19], 19
	s_add_u32 s20, s68, s20
	s_addc_u32 s21, s69, s21
	s_and_b64 s[22:23], s[0:1], exec
	s_cselect_b32 s19, s21, s25
	s_cselect_b32 s46, s20, s24
	s_ashr_i32 s17, s16, 31
	s_lshl_b64 s[22:23], s[16:17], 19
	v_readlane_b32 s30, v243, 24
	v_readlane_b32 s31, v243, 25
	s_add_u32 s22, s30, s22
	s_addc_u32 s23, s31, s23
	s_and_b64 s[30:31], s[0:1], exec
	v_mov_b32_e32 v2, v0
	v_mov_b32_e32 v3, v0
	s_cselect_b32 s17, s23, s29
	s_cselect_b32 s47, s22, s28
	s_add_u32 s48, s28, 0x100
	v_mov_b32_e32 v1, v0
	v_mov_b64_e32 v[6:7], v[2:3]
	v_mov_b64_e32 v[10:11], v[2:3]
	v_mov_b64_e32 v[22:23], v[2:3]
	v_mov_b64_e32 v[26:27], v[2:3]
	v_mov_b64_e32 v[38:39], v[2:3]
	v_mov_b64_e32 v[42:43], v[2:3]
	v_mov_b64_e32 v[54:55], v[2:3]
	v_mov_b64_e32 v[58:59], v[2:3]
	v_mov_b64_e32 v[14:15], v[2:3]
	v_mov_b64_e32 v[18:19], v[2:3]
	v_mov_b64_e32 v[30:31], v[2:3]
	v_mov_b64_e32 v[34:35], v[2:3]
	v_mov_b64_e32 v[46:47], v[2:3]
	v_mov_b64_e32 v[50:51], v[2:3]
	v_mov_b64_e32 v[62:63], v[2:3]
	v_mov_b64_e32 v[66:67], v[2:3]
	v_mov_b64_e32 v[70:71], v[2:3]
	v_mov_b64_e32 v[74:75], v[2:3]
	v_mov_b64_e32 v[86:87], v[2:3]
	v_mov_b64_e32 v[90:91], v[2:3]
	v_mov_b64_e32 v[102:103], v[2:3]
	v_mov_b64_e32 v[106:107], v[2:3]
	v_mov_b64_e32 v[118:119], v[2:3]
	v_mov_b64_e32 v[122:123], v[2:3]
	v_mov_b64_e32 v[78:79], v[2:3]
	v_mov_b64_e32 v[82:83], v[2:3]
	v_mov_b64_e32 v[94:95], v[2:3]
	v_mov_b64_e32 v[98:99], v[2:3]
	v_mov_b64_e32 v[110:111], v[2:3]
	v_mov_b64_e32 v[114:115], v[2:3]
	v_mov_b64_e32 v[126:127], v[2:3]
	v_mov_b64_e32 v[130:131], v[2:3]
	v_lshl_add_u32 v204, s26, 8, v223
	v_lshl_add_u32 v206, s27, 8, v225
	v_lshl_add_u64 v[208:209], s[24:25], 0, v[196:197]
	v_lshl_add_u64 v[210:211], s[24:25], 0, v[198:199]
	s_addc_u32 s49, s29, 0
	s_mov_b32 s50, -2
	s_mov_b64 s[26:27], 0
	v_mov_b64_e32 v[4:5], v[0:1]
	v_mov_b64_e32 v[8:9], v[0:1]
	v_mov_b64_e32 v[20:21], v[0:1]
	v_mov_b64_e32 v[24:25], v[0:1]
	v_mov_b64_e32 v[36:37], v[0:1]
	v_mov_b64_e32 v[40:41], v[0:1]
	v_mov_b64_e32 v[52:53], v[0:1]
	v_mov_b64_e32 v[56:57], v[0:1]
	v_mov_b64_e32 v[12:13], v[0:1]
	v_mov_b64_e32 v[16:17], v[0:1]
	v_mov_b64_e32 v[28:29], v[0:1]
	v_mov_b64_e32 v[32:33], v[0:1]
	v_mov_b64_e32 v[44:45], v[0:1]
	v_mov_b64_e32 v[48:49], v[0:1]
	v_mov_b64_e32 v[60:61], v[0:1]
	v_mov_b64_e32 v[64:65], v[0:1]
	v_mov_b64_e32 v[68:69], v[0:1]
	v_mov_b64_e32 v[72:73], v[0:1]
	v_mov_b64_e32 v[84:85], v[0:1]
	v_mov_b64_e32 v[88:89], v[0:1]
	v_mov_b64_e32 v[100:101], v[0:1]
	v_mov_b64_e32 v[104:105], v[0:1]
	v_mov_b64_e32 v[116:117], v[0:1]
	v_mov_b64_e32 v[120:121], v[0:1]
	v_mov_b64_e32 v[76:77], v[0:1]
	v_mov_b64_e32 v[80:81], v[0:1]
	v_mov_b64_e32 v[92:93], v[0:1]
	v_mov_b64_e32 v[96:97], v[0:1]
	v_mov_b64_e32 v[108:109], v[0:1]
	v_mov_b64_e32 v[112:113], v[0:1]
	v_mov_b64_e32 v[124:125], v[0:1]
	v_mov_b64_e32 v[128:129], v[0:1]
	s_branch .LBB0_3842
	s_nop 0
	s_nop 0
	s_nop 0
	s_nop 0
	s_nop 0
	s_nop 0
	s_nop 0
	s_nop 0
	s_nop 0
	s_nop 0
	s_nop 0
